# byte-phase pin B: the four rolled K-loop heads aligned to 64 bytes; rest as v166
# speedup vs baseline: 1.0066x; 1.0015x over previous
; #define PG8_STAGE(bufoff, gbase, voff) do { _Pragma("unroll") for (int _i = 0; _i < 2; ++_i) \
;         __builtin_amdgcn_global_load_lds((const unsigned*)((const char*)(gbase) + (voff)[_i]), (PG8_LAS unsigned*)(lds + (bufoff) + ldsw + _i * 8192), 16, 0, 0); } while (0)
; #define PG8_LDA(dst, b, h) do { _Pragma("unroll") for (int m = 0; m < 4; ++m) _Pragma("unroll") for (int k = 0; k < 2; ++k) dst[m][k] = *(const PG8_LAS bf16x8*)(lds + PG8_SA(b, h) + aoff + m * 2048 + k * 1024); } while (0)
; #define PG8_LDB(dst, b, h) do { _Pragma("unroll") for (int n = 0; n < 2; ++n) _Pragma("unroll") for (int k = 0; k < 2; ++k) dst[n][k] = *(const PG8_LAS bf16x8*)(lds + PG8_SB(b, h) + boff + n * 2048 + k * 1024); } while (0)
; #define PG8_WAIT_V(n) asm volatile("s_waitcnt vmcnt(" #n ")" ::: "memory")
; #define PG8_WAIT_L(n) asm volatile("s_waitcnt lgkmcnt(" #n ")" ::: "memory")
; #define PG8_BAR __builtin_amdgcn_s_barrier()
; #define PG8_SCHED __builtin_amdgcn_sched_barrier(0)
; template <class Epi, class Sched, bool ALIGN_EPI = false, bool SP2 = false>
; __device__ __forceinline__ void gemm_phase(PG8_LAS unsigned char* lds, const Gemm g, const Sched& S, const Epi& E, const int wave_id) {
;     ...
;         const char* nA = has_next ? (const char*)g.A + (size_t)nxt.pm * tstep : cA; const char* nB = has_next ? (const char*)g.Bt + (size_t)nxt.pn * tstep : cB;
;         for (int t = 0; t < nt; t += 2) {
;             const bool last = (t == nt - 2);
;             const char* a1 = cA + (size_t)(t + 1) * kstep;
;             const char* a2 = last ? nA : cA + (size_t)(t + 2) * kstep; const char* b2 = last ? nB : cB + (size_t)(t + 2) * kstep;
;             const char* a3 = a2 + kstep; const char* b3 = b2 + kstep;
;             if (last && has_next) S.a_ready(nxt);
;             if constexpr (SP2) {
;             PG8_LDB(B0, 0, 0); PG8_LDB(B1, 0, 1); PG8_SCHED; PG8_LDA(At, 0, 0); PG8_STAGE(PG8_SA(1, 1), a1 + hstep, voffA);
;             PG8_WAIT_V(8); PG8_WAIT_L(0); PG8_BAR; PG8_MMA(0, 0, At, B0); PG8_MMA(0, 1, At, B1); PG8_BAR; PG8_SCHED;
;     ...
; #pragma unroll
;         for (int a = 0; a < 2; ++a)
; #pragma unroll
;             for (int b = 0; b < 2; ++b)
; #pragma unroll
;                 for (int m = 0; m < 4; ++m)
; #pragma unroll
;                     for (int n = 0; n < 2; ++n) acc[a][b][m][n] = (f32x4){0.f, 0.f, 0.f, 0.f};
.LBB0_171:
	s_ashr_i32 s37, s36, 31
	s_lshl_b64 s[42:43], s[36:37], 20
	s_add_u32 s42, s10, s42
	s_addc_u32 s43, s11, s43
	s_and_b64 s[44:45], s[0:1], exec
	s_cselect_b32 s5, s43, s47
	s_cselect_b32 s7, s42, s46
	s_ashr_i32 s41, s40, 31
	s_lshl_b64 s[44:45], s[40:41], 20
	s_add_u32 s44, s62, s44
	s_addc_u32 s45, s63, s45
	s_and_b64 s[50:51], s[0:1], exec
	s_cselect_b32 s37, s45, s49
	s_cselect_b32 s41, s44, s48
	s_add_u32 s46, s46, 0x80080
	s_addc_u32 s47, s47, 0
	s_add_u32 s67, s48, 0x100
	v_mov_b32_e32 v0, 0
	s_addc_u32 s78, s49, 0
	s_mov_b32 s79, -2
	v_mov_b32_e32 v1, v0
	v_mov_b32_e32 v2, v0
	v_mov_b32_e32 v3, v0
	v_mov_b32_e32 v4, v0
	v_mov_b32_e32 v5, v0
	v_mov_b32_e32 v6, v0
	v_mov_b32_e32 v7, v0
	v_mov_b32_e32 v16, v0
	v_mov_b32_e32 v17, v0
	v_mov_b32_e32 v18, v0
	v_mov_b32_e32 v19, v0
	v_mov_b32_e32 v20, v0
	v_mov_b32_e32 v21, v0
	v_mov_b32_e32 v22, v0
	v_mov_b32_e32 v23, v0
	v_mov_b32_e32 v32, v0
	v_mov_b32_e32 v33, v0
	v_mov_b32_e32 v34, v0
	v_mov_b32_e32 v35, v0
	v_mov_b32_e32 v36, v0
	v_mov_b32_e32 v37, v0
	v_mov_b32_e32 v38, v0
	v_mov_b32_e32 v39, v0
	v_mov_b32_e32 v48, v0
	v_mov_b32_e32 v49, v0
	v_mov_b32_e32 v50, v0
	v_mov_b32_e32 v51, v0
	v_mov_b32_e32 v52, v0
	v_mov_b32_e32 v53, v0
	v_mov_b32_e32 v54, v0
	v_mov_b32_e32 v55, v0
	v_mov_b32_e32 v8, v0
	v_mov_b32_e32 v9, v0
	v_mov_b32_e32 v10, v0
	v_mov_b32_e32 v11, v0
	v_mov_b32_e32 v12, v0
	v_mov_b32_e32 v13, v0
	v_mov_b32_e32 v14, v0
	v_mov_b32_e32 v15, v0
	v_mov_b32_e32 v24, v0
	v_mov_b32_e32 v25, v0
	v_mov_b32_e32 v26, v0
	v_mov_b32_e32 v27, v0
	v_mov_b32_e32 v28, v0
	v_mov_b32_e32 v29, v0
	v_mov_b32_e32 v30, v0
	v_mov_b32_e32 v31, v0
	v_mov_b32_e32 v40, v0
	v_mov_b32_e32 v41, v0
	v_mov_b32_e32 v42, v0
	v_mov_b32_e32 v43, v0
	v_mov_b32_e32 v44, v0
	v_mov_b32_e32 v45, v0
	v_mov_b32_e32 v46, v0
	v_mov_b32_e32 v47, v0
	v_mov_b32_e32 v56, v0
	v_mov_b32_e32 v57, v0
	v_mov_b32_e32 v58, v0
	v_mov_b32_e32 v59, v0
	v_mov_b32_e32 v60, v0
	v_mov_b32_e32 v61, v0
	v_mov_b32_e32 v62, v0
	v_mov_b32_e32 v63, v0
	v_mov_b32_e32 v64, v0
	v_mov_b32_e32 v65, v0
	v_mov_b32_e32 v66, v0
	v_mov_b32_e32 v67, v0
	v_mov_b32_e32 v68, v0
	v_mov_b32_e32 v69, v0
	v_mov_b32_e32 v70, v0
	v_mov_b32_e32 v71, v0
	v_mov_b32_e32 v80, v0
	v_mov_b32_e32 v81, v0
	v_mov_b32_e32 v82, v0
	v_mov_b32_e32 v83, v0
	v_mov_b32_e32 v84, v0
	v_mov_b32_e32 v85, v0
	v_mov_b32_e32 v86, v0
	v_mov_b32_e32 v87, v0
	v_mov_b32_e32 v96, v0
	v_mov_b32_e32 v97, v0
	v_mov_b32_e32 v98, v0
	v_mov_b32_e32 v99, v0
	v_mov_b32_e32 v100, v0
	v_mov_b32_e32 v101, v0
	v_mov_b32_e32 v102, v0
	v_mov_b32_e32 v103, v0
	v_mov_b32_e32 v112, v0
	v_mov_b32_e32 v113, v0
	v_mov_b32_e32 v114, v0
	v_mov_b32_e32 v115, v0
	v_mov_b32_e32 v116, v0
	v_mov_b32_e32 v117, v0
	v_mov_b32_e32 v118, v0
	v_mov_b32_e32 v119, v0
	v_mov_b32_e32 v72, v0
	v_mov_b32_e32 v73, v0
	v_mov_b32_e32 v74, v0
	v_mov_b32_e32 v75, v0
	v_mov_b32_e32 v76, v0
	v_mov_b32_e32 v77, v0
	v_mov_b32_e32 v78, v0
	v_mov_b32_e32 v79, v0
	v_mov_b32_e32 v88, v0
	v_mov_b32_e32 v89, v0
	v_mov_b32_e32 v90, v0
	v_mov_b32_e32 v91, v0
	v_mov_b32_e32 v92, v0
	v_mov_b32_e32 v93, v0
	v_mov_b32_e32 v94, v0
	v_mov_b32_e32 v95, v0
	v_mov_b32_e32 v104, v0
	v_mov_b32_e32 v105, v0
	v_mov_b32_e32 v106, v0
	v_mov_b32_e32 v107, v0
	v_mov_b32_e32 v108, v0
	v_mov_b32_e32 v109, v0
	v_mov_b32_e32 v110, v0
	v_mov_b32_e32 v111, v0
	v_mov_b32_e32 v120, v0
	v_mov_b32_e32 v121, v0
	v_mov_b32_e32 v122, v0
	v_mov_b32_e32 v123, v0
	v_mov_b32_e32 v124, v0
	v_mov_b32_e32 v125, v0
	v_mov_b32_e32 v126, v0
	v_mov_b32_e32 v127, v0
	s_nop 0
	s_nop 0
	s_nop 0
	s_nop 0
	s_nop 0
	s_nop 0
	s_nop 0
.LBB0_172:
	ds_read_b128 v[148:151], v159
	ds_read_b128 v[152:155], v159 offset:1024
	ds_read_b128 v[162:165], v159 offset:2048
	ds_read_b128 v[166:169], v159 offset:3072
	ds_read_b128 v[170:173], v160
	ds_read_b128 v[174:177], v160 offset:1024
	ds_read_b128 v[178:181], v160 offset:2048
	ds_read_b128 v[182:185], v160 offset:3072
	s_add_u32 s48, s46, 0xfff80080
	s_addc_u32 s49, s47, -1
	s_cmp_eq_u32 s79, 28
	s_cselect_b32 s51, s5, s49
	s_cselect_b32 s50, s7, s48
	s_cselect_b32 s49, s37, s78
	s_cselect_b32 s48, s41, s67
	v_lshl_add_u64 v[218:219], s[46:47], 0, v[138:139]
	s_add_i32 m0, s68, 0xc000
	ds_read_b128 v[186:189], v161
	ds_read_b128 v[190:193], v161 offset:1024
	ds_read_b128 v[194:197], v161 offset:2048
	ds_read_b128 v[198:201], v161 offset:3072
	ds_read_b128 v[202:205], v161 offset:4096
	ds_read_b128 v[206:209], v161 offset:5120
	ds_read_b128 v[210:213], v161 offset:6144
	ds_read_b128 v[214:217], v161 offset:7168
	global_load_lds_dwordx4 v[218:219], off
	v_lshl_add_u64 v[218:219], s[46:47], 0, v[140:141]
	s_add_i32 m0, s68, 0xe000
	s_nop 0
	global_load_lds_dwordx4 v[218:219], off
	s_waitcnt vmcnt(8)
	s_waitcnt lgkmcnt(0)
	s_barrier
; #define PG8_STAGE(bufoff, gbase, voff) do { _Pragma("unroll") for (int _i = 0; _i < 2; ++_i) \
;         __builtin_amdgcn_global_load_lds((const unsigned*)((const char*)(gbase) + (voff)[_i]), (PG8_LAS unsigned*)(lds + (bufoff) + ldsw + _i * 8192), 16, 0, 0); } while (0)
; #define PG8_LDA(dst, b, h) do { _Pragma("unroll") for (int m = 0; m < 4; ++m) _Pragma("unroll") for (int k = 0; k < 2; ++k) dst[m][k] = *(const PG8_LAS bf16x8*)(lds + PG8_SA(b, h) + aoff + m * 2048 + k * 1024); } while (0)
; #define PG8_MMA(ai, bj, At, Bt) do { __builtin_amdgcn_s_setprio(1); _Pragma("unroll") for (int m = 0; m < 4; ++m) _Pragma("unroll") for (int n = 0; n < 2; ++n) _Pragma("unroll") for (int k = 0; k < 2; ++k) \
;         acc[ai][bj][m][n] = __builtin_amdgcn_mfma_f32_16x16x32_bf16(Bt[n][k], At[m][k], acc[ai][bj][m][n], 0, 0, 0); __builtin_amdgcn_s_setprio(0); } while (0)
; #define PG8_WAIT_V(n) asm volatile("s_waitcnt vmcnt(" #n ")" ::: "memory")
; #define PG8_WAIT_L(n) asm volatile("s_waitcnt lgkmcnt(" #n ")" ::: "memory")
; #define PG8_BAR __builtin_amdgcn_s_barrier()
; #define PG8_SCHED __builtin_amdgcn_sched_barrier(0)
; template <class Epi, class Sched, bool ALIGN_EPI = false, bool SP2 = false>
; __device__ __forceinline__ void gemm_phase(PG8_LAS unsigned char* lds, const Gemm g, const Sched& S, const Epi& E, const int wave_id) {
;     ...
;             PG8_WAIT_V(8); PG8_WAIT_L(0); PG8_BAR; PG8_MMA(0, 0, At, B0); PG8_MMA(0, 1, At, B1); PG8_BAR; PG8_SCHED;
;             PG8_LDA(At, 0, 1); PG8_STAGE(PG8_SB(0, 0), b2, voffB); PG8_STAGE(PG8_SB(0, 1), b2 + hstep, voffB); PG8_STAGE(PG8_SA(0, 0), a2, voffA);
;             PG8_WAIT_V(8); PG8_WAIT_L(0); PG8_BAR; PG8_MMA(1, 0, At, B0); PG8_MMA(1, 1, At, B1); PG8_BAR; PG8_SCHED;
	s_waitcnt lgkmcnt(0)
	v_mfma_f32_16x16x32_bf16 v[124:127], v[148:151], v[186:189], v[124:127]
	v_mfma_f32_16x16x32_bf16 v[120:123], v[162:165], v[186:189], v[120:123]
	v_mfma_f32_16x16x32_bf16 v[108:111], v[148:151], v[194:197], v[108:111]
	v_mfma_f32_16x16x32_bf16 v[104:107], v[162:165], v[194:197], v[104:107]
	v_mfma_f32_16x16x32_bf16 v[92:95], v[148:151], v[202:205], v[92:95]
	v_mfma_f32_16x16x32_bf16 v[88:91], v[162:165], v[202:205], v[88:91]
	v_mfma_f32_16x16x32_bf16 v[76:79], v[148:151], v[210:213], v[76:79]
	v_mfma_f32_16x16x32_bf16 v[72:75], v[162:165], v[210:213], v[72:75]
	v_mfma_f32_16x16x32_bf16 v[124:127], v[152:155], v[190:193], v[124:127]
	v_mfma_f32_16x16x32_bf16 v[120:123], v[166:169], v[190:193], v[120:123]
	v_mfma_f32_16x16x32_bf16 v[108:111], v[152:155], v[198:201], v[108:111]
	v_mfma_f32_16x16x32_bf16 v[104:107], v[166:169], v[198:201], v[104:107]
	v_mfma_f32_16x16x32_bf16 v[92:95], v[152:155], v[206:209], v[92:95]
	v_mfma_f32_16x16x32_bf16 v[88:91], v[166:169], v[206:209], v[88:91]
	v_mfma_f32_16x16x32_bf16 v[76:79], v[152:155], v[214:217], v[76:79]
	v_mfma_f32_16x16x32_bf16 v[72:75], v[166:169], v[214:217], v[72:75]
	v_mfma_f32_16x16x32_bf16 v[116:119], v[170:173], v[186:189], v[116:119]
	v_mfma_f32_16x16x32_bf16 v[112:115], v[178:181], v[186:189], v[112:115]
	v_mfma_f32_16x16x32_bf16 v[100:103], v[170:173], v[194:197], v[100:103]
	v_mfma_f32_16x16x32_bf16 v[96:99], v[178:181], v[194:197], v[96:99]
	v_mfma_f32_16x16x32_bf16 v[84:87], v[170:173], v[202:205], v[84:87]
	v_mfma_f32_16x16x32_bf16 v[80:83], v[178:181], v[202:205], v[80:83]
	v_mfma_f32_16x16x32_bf16 v[68:71], v[170:173], v[210:213], v[68:71]
	v_mfma_f32_16x16x32_bf16 v[64:67], v[178:181], v[210:213], v[64:67]
	v_mfma_f32_16x16x32_bf16 v[116:119], v[174:177], v[190:193], v[116:119]
	v_mfma_f32_16x16x32_bf16 v[112:115], v[182:185], v[190:193], v[112:115]
	v_mfma_f32_16x16x32_bf16 v[100:103], v[174:177], v[198:201], v[100:103]
	v_mfma_f32_16x16x32_bf16 v[96:99], v[182:185], v[198:201], v[96:99]
	v_mfma_f32_16x16x32_bf16 v[84:87], v[174:177], v[206:209], v[84:87]
	v_mfma_f32_16x16x32_bf16 v[80:83], v[182:185], v[206:209], v[80:83]
	v_mfma_f32_16x16x32_bf16 v[68:71], v[174:177], v[214:217], v[68:71]
	v_mfma_f32_16x16x32_bf16 v[64:67], v[182:185], v[214:217], v[64:67]
	s_barrier
	s_add_i32 s80, s76, s56
	v_lshl_add_u64 v[218:219], s[48:49], 0, v[130:131]
	s_mov_b32 m0, s80
	ds_read_b128 v[186:189], v161 offset:16384
	ds_read_b128 v[190:193], v161 offset:17408
	ds_read_b128 v[194:197], v161 offset:18432
	ds_read_b128 v[198:201], v161 offset:19456
	ds_read_b128 v[202:205], v161 offset:20480
	ds_read_b128 v[206:209], v161 offset:21504
	ds_read_b128 v[210:213], v161 offset:22528
	ds_read_b128 v[214:217], v161 offset:23552
	global_load_lds_dwordx4 v[218:219], off
	s_add_i32 m0, s80, 0x2000
	s_add_u32 s80, s48, 0x80000
	v_lshl_add_u64 v[220:221], s[48:49], 0, v[134:135]
	s_addc_u32 s81, s49, 0
	s_add_i32 s82, s77, s56
	global_load_lds_dwordx4 v[220:221], off
	v_lshl_add_u64 v[222:223], s[80:81], 0, v[130:131]
	s_mov_b32 m0, s82
	v_lshl_add_u64 v[224:225], s[50:51], 0, v[132:133]
	global_load_lds_dwordx4 v[222:223], off
	v_lshl_add_u64 v[222:223], s[80:81], 0, v[134:135]
	s_add_i32 m0, s82, 0x2000
	s_nop 0
	global_load_lds_dwordx4 v[222:223], off
	v_lshl_add_u64 v[222:223], s[50:51], 0, v[128:129]
	s_mov_b32 m0, s68
	s_nop 0
	global_load_lds_dwordx4 v[222:223], off
	s_mov_b32 m0, s70
	s_nop 0
	global_load_lds_dwordx4 v[224:225], off
	s_waitcnt vmcnt(8)
	s_waitcnt lgkmcnt(0)
	s_barrier
	s_waitcnt lgkmcnt(0)
	v_mfma_f32_16x16x32_bf16 v[60:63], v[148:151], v[186:189], v[60:63]
	v_mfma_f32_16x16x32_bf16 v[56:59], v[162:165], v[186:189], v[56:59]
	v_mfma_f32_16x16x32_bf16 v[44:47], v[148:151], v[194:197], v[44:47]
	v_mfma_f32_16x16x32_bf16 v[40:43], v[162:165], v[194:197], v[40:43]
	v_mfma_f32_16x16x32_bf16 v[28:31], v[148:151], v[202:205], v[28:31]
	v_mfma_f32_16x16x32_bf16 v[24:27], v[162:165], v[202:205], v[24:27]
	v_mfma_f32_16x16x32_bf16 v[12:15], v[148:151], v[210:213], v[12:15]
	v_mfma_f32_16x16x32_bf16 v[8:11], v[162:165], v[210:213], v[8:11]
	v_mfma_f32_16x16x32_bf16 v[60:63], v[152:155], v[190:193], v[60:63]
	v_mfma_f32_16x16x32_bf16 v[56:59], v[166:169], v[190:193], v[56:59]
	v_mfma_f32_16x16x32_bf16 v[44:47], v[152:155], v[198:201], v[44:47]
	v_mfma_f32_16x16x32_bf16 v[40:43], v[166:169], v[198:201], v[40:43]
	v_mfma_f32_16x16x32_bf16 v[28:31], v[152:155], v[206:209], v[28:31]
	v_mfma_f32_16x16x32_bf16 v[24:27], v[166:169], v[206:209], v[24:27]
	v_mfma_f32_16x16x32_bf16 v[12:15], v[152:155], v[214:217], v[12:15]
	v_mfma_f32_16x16x32_bf16 v[8:11], v[166:169], v[214:217], v[8:11]
	v_mfma_f32_16x16x32_bf16 v[52:55], v[170:173], v[186:189], v[52:55]
	v_mfma_f32_16x16x32_bf16 v[48:51], v[178:181], v[186:189], v[48:51]
	v_mfma_f32_16x16x32_bf16 v[36:39], v[170:173], v[194:197], v[36:39]
	v_mfma_f32_16x16x32_bf16 v[32:35], v[178:181], v[194:197], v[32:35]
	v_mfma_f32_16x16x32_bf16 v[20:23], v[170:173], v[202:205], v[20:23]
	v_mfma_f32_16x16x32_bf16 v[16:19], v[178:181], v[202:205], v[16:19]
	v_mfma_f32_16x16x32_bf16 v[4:7], v[170:173], v[210:213], v[4:7]
	v_mfma_f32_16x16x32_bf16 v[0:3], v[178:181], v[210:213], v[0:3]
	v_mfma_f32_16x16x32_bf16 v[52:55], v[174:177], v[190:193], v[52:55]
	v_mfma_f32_16x16x32_bf16 v[48:51], v[182:185], v[190:193], v[48:51]
	v_mfma_f32_16x16x32_bf16 v[36:39], v[174:177], v[198:201], v[36:39]
	v_mfma_f32_16x16x32_bf16 v[32:35], v[182:185], v[198:201], v[32:35]
	v_mfma_f32_16x16x32_bf16 v[20:23], v[174:177], v[206:209], v[20:23]
	v_mfma_f32_16x16x32_bf16 v[16:19], v[182:185], v[206:209], v[16:19]
	v_mfma_f32_16x16x32_bf16 v[4:7], v[174:177], v[214:217], v[4:7]
	v_mfma_f32_16x16x32_bf16 v[0:3], v[182:185], v[214:217], v[0:3]
	s_barrier
; #define PG8_STAGE(bufoff, gbase, voff) do { _Pragma("unroll") for (int _i = 0; _i < 2; ++_i) \
;         __builtin_amdgcn_global_load_lds((const unsigned*)((const char*)(gbase) + (voff)[_i]), (PG8_LAS unsigned*)(lds + (bufoff) + ldsw + _i * 8192), 16, 0, 0); } while (0)
; #define PG8_LDA(dst, b, h) do { _Pragma("unroll") for (int m = 0; m < 4; ++m) _Pragma("unroll") for (int k = 0; k < 2; ++k) dst[m][k] = *(const PG8_LAS bf16x8*)(lds + PG8_SA(b, h) + aoff + m * 2048 + k * 1024); } while (0)
; #define PG8_LDB(dst, b, h) do { _Pragma("unroll") for (int n = 0; n < 2; ++n) _Pragma("unroll") for (int k = 0; k < 2; ++k) dst[n][k] = *(const PG8_LAS bf16x8*)(lds + PG8_SB(b, h) + boff + n * 2048 + k * 1024); } while (0)
; #define PG8_MMA(ai, bj, At, Bt) do { __builtin_amdgcn_s_setprio(1); _Pragma("unroll") for (int m = 0; m < 4; ++m) _Pragma("unroll") for (int n = 0; n < 2; ++n) _Pragma("unroll") for (int k = 0; k < 2; ++k) \
;         acc[ai][bj][m][n] = __builtin_amdgcn_mfma_f32_16x16x32_bf16(Bt[n][k], At[m][k], acc[ai][bj][m][n], 0, 0, 0); __builtin_amdgcn_s_setprio(0); } while (0)
; #define PG8_WAIT_V(n) asm volatile("s_waitcnt vmcnt(" #n ")" ::: "memory")
; #define PG8_WAIT_L(n) asm volatile("s_waitcnt lgkmcnt(" #n ")" ::: "memory")
; #define PG8_BAR __builtin_amdgcn_s_barrier()
; #define PG8_SCHED __builtin_amdgcn_sched_barrier(0)
; template <class Epi, class Sched, bool ALIGN_EPI = false, bool SP2 = false>
; __device__ __forceinline__ void gemm_phase(PG8_LAS unsigned char* lds, const Gemm g, const Sched& S, const Epi& E, const int wave_id) {
;     ...
;             PG8_LDB(B0, 1, 0); PG8_LDB(B1, 1, 1); PG8_SCHED; PG8_LDA(At, 1, 0); PG8_STAGE(PG8_SA(0, 1), a2 + hstep, voffA);
;             PG8_WAIT_V(8); PG8_WAIT_L(0); PG8_BAR; PG8_MMA(0, 0, At, B0); PG8_MMA(0, 1, At, B1); PG8_BAR; PG8_SCHED;
	s_add_i32 s80, 0, 0x18000
	v_add_u32_e32 v136, s80, v157
	s_add_i32 s81, 0, 0x1c000
	ds_read_b128 v[148:151], v136
	ds_read_b128 v[152:155], v136 offset:1024
	ds_read_b128 v[162:165], v136 offset:2048
	ds_read_b128 v[166:169], v136 offset:3072
	v_add_u32_e32 v136, s81, v157
	ds_read_b128 v[170:173], v136
	ds_read_b128 v[174:177], v136 offset:1024
	ds_read_b128 v[178:181], v136 offset:2048
	ds_read_b128 v[182:185], v136 offset:3072
	s_add_u32 s50, s50, 0x80000
	s_addc_u32 s51, s51, 0
	s_mov_b32 m0, s71
	v_lshl_add_u64 v[226:227], s[50:51], 0, v[128:129]
	ds_read_b128 v[186:189], v161 offset:32768
	ds_read_b128 v[190:193], v161 offset:33792
	ds_read_b128 v[194:197], v161 offset:34816
	ds_read_b128 v[198:201], v161 offset:35840
	ds_read_b128 v[202:205], v161 offset:36864
	ds_read_b128 v[206:209], v161 offset:37888
	ds_read_b128 v[210:213], v161 offset:38912
	ds_read_b128 v[214:217], v161 offset:39936
	global_load_lds_dwordx4 v[226:227], off
	v_lshl_add_u64 v[226:227], s[50:51], 0, v[132:133]
	s_mov_b32 m0, s72
	s_nop 0
	global_load_lds_dwordx4 v[226:227], off
	s_waitcnt vmcnt(8)
	s_waitcnt lgkmcnt(0)
	s_barrier
	s_waitcnt lgkmcnt(0)
	v_mfma_f32_16x16x32_bf16 v[124:127], v[148:151], v[186:189], v[124:127]
	v_mfma_f32_16x16x32_bf16 v[120:123], v[162:165], v[186:189], v[120:123]
	v_mfma_f32_16x16x32_bf16 v[108:111], v[148:151], v[194:197], v[108:111]
	v_mfma_f32_16x16x32_bf16 v[104:107], v[162:165], v[194:197], v[104:107]
	v_mfma_f32_16x16x32_bf16 v[92:95], v[148:151], v[202:205], v[92:95]
	v_mfma_f32_16x16x32_bf16 v[88:91], v[162:165], v[202:205], v[88:91]
	v_mfma_f32_16x16x32_bf16 v[76:79], v[148:151], v[210:213], v[76:79]
	v_mfma_f32_16x16x32_bf16 v[72:75], v[162:165], v[210:213], v[72:75]
	v_mfma_f32_16x16x32_bf16 v[124:127], v[152:155], v[190:193], v[124:127]
	v_mfma_f32_16x16x32_bf16 v[120:123], v[166:169], v[190:193], v[120:123]
	v_mfma_f32_16x16x32_bf16 v[108:111], v[152:155], v[198:201], v[108:111]
	v_mfma_f32_16x16x32_bf16 v[104:107], v[166:169], v[198:201], v[104:107]
	v_mfma_f32_16x16x32_bf16 v[92:95], v[152:155], v[206:209], v[92:95]
	v_mfma_f32_16x16x32_bf16 v[88:91], v[166:169], v[206:209], v[88:91]
	v_mfma_f32_16x16x32_bf16 v[76:79], v[152:155], v[214:217], v[76:79]
	v_mfma_f32_16x16x32_bf16 v[72:75], v[166:169], v[214:217], v[72:75]
	v_mfma_f32_16x16x32_bf16 v[116:119], v[170:173], v[186:189], v[116:119]
	v_mfma_f32_16x16x32_bf16 v[112:115], v[178:181], v[186:189], v[112:115]
	v_mfma_f32_16x16x32_bf16 v[100:103], v[170:173], v[194:197], v[100:103]
	v_mfma_f32_16x16x32_bf16 v[96:99], v[178:181], v[194:197], v[96:99]
	v_mfma_f32_16x16x32_bf16 v[84:87], v[170:173], v[202:205], v[84:87]
	v_mfma_f32_16x16x32_bf16 v[80:83], v[178:181], v[202:205], v[80:83]
	v_mfma_f32_16x16x32_bf16 v[68:71], v[170:173], v[210:213], v[68:71]
	v_mfma_f32_16x16x32_bf16 v[64:67], v[178:181], v[210:213], v[64:67]
	v_mfma_f32_16x16x32_bf16 v[116:119], v[174:177], v[190:193], v[116:119]
	v_mfma_f32_16x16x32_bf16 v[112:115], v[182:185], v[190:193], v[112:115]
	v_mfma_f32_16x16x32_bf16 v[100:103], v[174:177], v[198:201], v[100:103]
	v_mfma_f32_16x16x32_bf16 v[96:99], v[182:185], v[198:201], v[96:99]
	v_mfma_f32_16x16x32_bf16 v[84:87], v[174:177], v[206:209], v[84:87]
	v_mfma_f32_16x16x32_bf16 v[80:83], v[182:185], v[206:209], v[80:83]
	v_mfma_f32_16x16x32_bf16 v[68:71], v[174:177], v[214:217], v[68:71]
	v_mfma_f32_16x16x32_bf16 v[64:67], v[182:185], v[214:217], v[64:67]
	s_barrier
; #define PG8_STAGE(bufoff, gbase, voff) do { _Pragma("unroll") for (int _i = 0; _i < 2; ++_i) \
;         __builtin_amdgcn_global_load_lds((const unsigned*)((const char*)(gbase) + (voff)[_i]), (PG8_LAS unsigned*)(lds + (bufoff) + ldsw + _i * 8192), 16, 0, 0); } while (0)
; #define PG8_LDA(dst, b, h) do { _Pragma("unroll") for (int m = 0; m < 4; ++m) _Pragma("unroll") for (int k = 0; k < 2; ++k) dst[m][k] = *(const PG8_LAS bf16x8*)(lds + PG8_SA(b, h) + aoff + m * 2048 + k * 1024); } while (0)
; #define PG8_MMA(ai, bj, At, Bt) do { __builtin_amdgcn_s_setprio(1); _Pragma("unroll") for (int m = 0; m < 4; ++m) _Pragma("unroll") for (int n = 0; n < 2; ++n) _Pragma("unroll") for (int k = 0; k < 2; ++k) \
;         acc[ai][bj][m][n] = __builtin_amdgcn_mfma_f32_16x16x32_bf16(Bt[n][k], At[m][k], acc[ai][bj][m][n], 0, 0, 0); __builtin_amdgcn_s_setprio(0); } while (0)
; #define PG8_WAIT_V(n) asm volatile("s_waitcnt vmcnt(" #n ")" ::: "memory")
; #define PG8_WAIT_L(n) asm volatile("s_waitcnt lgkmcnt(" #n ")" ::: "memory")
; #define PG8_BAR __builtin_amdgcn_s_barrier()
; #define PG8_SCHED __builtin_amdgcn_sched_barrier(0)
; template <class Epi, class Sched, bool ALIGN_EPI = false, bool SP2 = false>
; __device__ __forceinline__ void gemm_phase(PG8_LAS unsigned char* lds, const Gemm g, const Sched& S, const Epi& E, const int wave_id) {
;     ...
;             PG8_LDA(At, 1, 1); PG8_STAGE(PG8_SB(1, 0), b3, voffB); PG8_STAGE(PG8_SB(1, 1), b3 + hstep, voffB); PG8_STAGE(PG8_SA(1, 0), a3, voffA);
;             PG8_WAIT_V(8); PG8_WAIT_L(0); PG8_BAR; PG8_MMA(1, 0, At, B0); PG8_MMA(1, 1, At, B1); PG8_BAR; PG8_SCHED;
	s_add_i32 s50, s80, s56
	v_lshl_add_u64 v[218:219], v[218:219], 0, s[16:17]
	s_mov_b32 m0, s50
	ds_read_b128 v[186:189], v161 offset:49152
	ds_read_b128 v[190:193], v161 offset:50176
	ds_read_b128 v[194:197], v161 offset:51200
	ds_read_b128 v[198:201], v161 offset:52224
	ds_read_b128 v[202:205], v161 offset:53248
	ds_read_b128 v[206:209], v161 offset:54272
	ds_read_b128 v[210:213], v161 offset:55296
	ds_read_b128 v[214:217], v161 offset:56320
	global_load_lds_dwordx4 v[218:219], off
	s_add_i32 m0, s50, 0x2000
	s_add_u32 s48, s48, 0x80080
	v_lshl_add_u64 v[218:219], v[220:221], 0, s[16:17]
	s_addc_u32 s49, s49, 0
	s_add_i32 s50, s81, s56
	global_load_lds_dwordx4 v[218:219], off
	v_lshl_add_u64 v[218:219], s[48:49], 0, v[130:131]
	s_mov_b32 m0, s50
	s_nop 0
	global_load_lds_dwordx4 v[218:219], off
	v_lshl_add_u64 v[218:219], s[48:49], 0, v[134:135]
	s_add_i32 m0, s50, 0x2000
	s_nop 0
	global_load_lds_dwordx4 v[218:219], off
	v_lshl_add_u64 v[218:219], v[222:223], 0, s[16:17]
	s_mov_b32 m0, s73
	s_nop 0
	global_load_lds_dwordx4 v[218:219], off
	v_lshl_add_u64 v[218:219], v[224:225], 0, s[16:17]
	s_mov_b32 m0, s74
	s_nop 0
	global_load_lds_dwordx4 v[218:219], off
	s_waitcnt vmcnt(8)
	s_waitcnt lgkmcnt(0)
	s_barrier
	s_waitcnt lgkmcnt(0)
	v_mfma_f32_16x16x32_bf16 v[60:63], v[148:151], v[186:189], v[60:63]
	v_mfma_f32_16x16x32_bf16 v[56:59], v[162:165], v[186:189], v[56:59]
	v_mfma_f32_16x16x32_bf16 v[44:47], v[148:151], v[194:197], v[44:47]
	v_mfma_f32_16x16x32_bf16 v[40:43], v[162:165], v[194:197], v[40:43]
	v_mfma_f32_16x16x32_bf16 v[28:31], v[148:151], v[202:205], v[28:31]
	v_mfma_f32_16x16x32_bf16 v[24:27], v[162:165], v[202:205], v[24:27]
	v_mfma_f32_16x16x32_bf16 v[12:15], v[148:151], v[210:213], v[12:15]
	v_mfma_f32_16x16x32_bf16 v[8:11], v[162:165], v[210:213], v[8:11]
	v_mfma_f32_16x16x32_bf16 v[60:63], v[152:155], v[190:193], v[60:63]
	v_mfma_f32_16x16x32_bf16 v[56:59], v[166:169], v[190:193], v[56:59]
	v_mfma_f32_16x16x32_bf16 v[44:47], v[152:155], v[198:201], v[44:47]
	v_mfma_f32_16x16x32_bf16 v[40:43], v[166:169], v[198:201], v[40:43]
	v_mfma_f32_16x16x32_bf16 v[28:31], v[152:155], v[206:209], v[28:31]
	v_mfma_f32_16x16x32_bf16 v[24:27], v[166:169], v[206:209], v[24:27]
	v_mfma_f32_16x16x32_bf16 v[12:15], v[152:155], v[214:217], v[12:15]
	v_mfma_f32_16x16x32_bf16 v[8:11], v[166:169], v[214:217], v[8:11]
	v_mfma_f32_16x16x32_bf16 v[52:55], v[170:173], v[186:189], v[52:55]
	v_mfma_f32_16x16x32_bf16 v[48:51], v[178:181], v[186:189], v[48:51]
	v_mfma_f32_16x16x32_bf16 v[36:39], v[170:173], v[194:197], v[36:39]
	v_mfma_f32_16x16x32_bf16 v[32:35], v[178:181], v[194:197], v[32:35]
	v_mfma_f32_16x16x32_bf16 v[20:23], v[170:173], v[202:205], v[20:23]
	v_mfma_f32_16x16x32_bf16 v[16:19], v[178:181], v[202:205], v[16:19]
	v_mfma_f32_16x16x32_bf16 v[4:7], v[170:173], v[210:213], v[4:7]
	v_mfma_f32_16x16x32_bf16 v[0:3], v[178:181], v[210:213], v[0:3]
	v_mfma_f32_16x16x32_bf16 v[52:55], v[174:177], v[190:193], v[52:55]
	v_mfma_f32_16x16x32_bf16 v[48:51], v[182:185], v[190:193], v[48:51]
	v_mfma_f32_16x16x32_bf16 v[36:39], v[174:177], v[198:201], v[36:39]
	v_mfma_f32_16x16x32_bf16 v[32:35], v[182:185], v[198:201], v[32:35]
	v_mfma_f32_16x16x32_bf16 v[20:23], v[174:177], v[206:209], v[20:23]
	v_mfma_f32_16x16x32_bf16 v[16:19], v[182:185], v[206:209], v[16:19]
	v_mfma_f32_16x16x32_bf16 v[4:7], v[174:177], v[214:217], v[4:7]
	v_mfma_f32_16x16x32_bf16 v[0:3], v[182:185], v[214:217], v[0:3]
	s_barrier
	s_add_i32 s79, s79, 2
	s_add_u32 s46, s46, 0x100
	s_addc_u32 s47, s47, 0
	s_add_u32 s67, s67, 0x100
	s_addc_u32 s78, s78, 0
	s_cmp_gt_u32 s79, 29
	s_cbranch_scc0 .LBB0_172
	s_and_b64 vcc, exec, s[24:25]
	s_cbranch_vccz .LBB0_175
	s_barrier

;     __device__ __forceinline__ bool next(int i, Unit& u) const { if (i != 0) return false; return base.next(which, u); }
;     __device__ __forceinline__ bool next(int i, Unit& u) const { if (i >= nrd) return false; u.pm = (rd0 + i) * 16 + 4 * xl + (j >> 3); u.pn = j & 7; return true; }
; template <class Epi, class Sched, bool ALIGN_EPI = false, bool SP2 = false>
; __device__ __forceinline__ void gemm_phase(PG8_LAS unsigned char* lds, const Gemm g, const Sched& S, const Epi& E, const int wave_id) {
;     ...
;         const bool has_next = S.next(ui + 1, nxt);
;         const char* nA = has_next ? (const char*)g.A + (size_t)nxt.pm * tstep : cA; const char* nB = has_next ? (const char*)g.Bt + (size_t)nxt.pn * tstep : cB;
;     ...
; #pragma unroll
;         for (int a = 0; a < 2; ++a)
; #pragma unroll
;             for (int b = 0; b < 2; ++b)
; #pragma unroll
;                 for (int m = 0; m < 4; ++m)
; #pragma unroll
;                     for (int n = 0; n < 2; ++n) acc[a][b][m][n] = (f32x4){0.f, 0.f, 0.f, 0.f};
;         cur = nxt; cA = nA; cB = nB; ++ui;
.LBB0_449:
	s_mov_b32 s24, s42
	s_mov_b32 s0, s42
	s_add_i32 s42, s1, s12
	s_mov_b64 s[22:23], s[14:15]
	s_and_b64 s[14:15], s[20:21], exec
	s_cselect_b32 s14, s42, s24
	s_ashr_i32 s15, s14, 31
	s_lshl_b64 s[14:15], s[14:15], 19
	s_add_u32 s14, s38, s14
	s_addc_u32 s15, s39, s15
	s_and_b64 s[24:25], s[20:21], exec
	v_mov_b32_e32 v0, 0
	s_cselect_b32 s1, s15, s23
	s_cselect_b32 s43, s14, s22
	v_lshl_add_u64 v[112:113], s[22:23], 0, v[172:173]
	v_lshl_add_u64 v[114:115], s[22:23], 0, v[174:175]
	s_mov_b32 s44, -2
	s_mov_b64 s[24:25], 0
	v_mov_b32_e32 v1, v0
	v_mov_b32_e32 v2, v0
	v_mov_b32_e32 v3, v0
	v_mov_b32_e32 v8, v0
	v_mov_b32_e32 v9, v0
	v_mov_b32_e32 v10, v0
	v_mov_b32_e32 v11, v0
	v_mov_b32_e32 v16, v0
	v_mov_b32_e32 v17, v0
	v_mov_b32_e32 v18, v0
	v_mov_b32_e32 v19, v0
	v_mov_b32_e32 v24, v0
	v_mov_b32_e32 v25, v0
	v_mov_b32_e32 v26, v0
	v_mov_b32_e32 v27, v0
	v_mov_b32_e32 v32, v0
	v_mov_b32_e32 v33, v0
	v_mov_b32_e32 v34, v0
	v_mov_b32_e32 v35, v0
	v_mov_b32_e32 v40, v0
	v_mov_b32_e32 v41, v0
	v_mov_b32_e32 v42, v0
	v_mov_b32_e32 v43, v0
	v_mov_b32_e32 v48, v0
	v_mov_b32_e32 v49, v0
	v_mov_b32_e32 v50, v0
	v_mov_b32_e32 v51, v0
	v_mov_b32_e32 v56, v0
	v_mov_b32_e32 v57, v0
	v_mov_b32_e32 v58, v0
	v_mov_b32_e32 v59, v0
	v_mov_b32_e32 v4, v0
	v_mov_b32_e32 v5, v0
	v_mov_b32_e32 v6, v0
	v_mov_b32_e32 v7, v0
	v_mov_b32_e32 v12, v0
	v_mov_b32_e32 v13, v0
	v_mov_b32_e32 v14, v0
	v_mov_b32_e32 v15, v0
	v_mov_b32_e32 v20, v0
	v_mov_b32_e32 v21, v0
	v_mov_b32_e32 v22, v0
	v_mov_b32_e32 v23, v0
	v_mov_b32_e32 v28, v0
	v_mov_b32_e32 v29, v0
	v_mov_b32_e32 v30, v0
	v_mov_b32_e32 v31, v0
	v_mov_b32_e32 v36, v0
	v_mov_b32_e32 v37, v0
	v_mov_b32_e32 v38, v0
	v_mov_b32_e32 v39, v0
	v_mov_b32_e32 v44, v0
	v_mov_b32_e32 v45, v0
	v_mov_b32_e32 v46, v0
	v_mov_b32_e32 v47, v0
	v_mov_b32_e32 v52, v0
	v_mov_b32_e32 v53, v0
	v_mov_b32_e32 v54, v0
	v_mov_b32_e32 v55, v0
	v_mov_b32_e32 v60, v0
	v_mov_b32_e32 v61, v0
	v_mov_b32_e32 v62, v0
	v_mov_b32_e32 v63, v0
	v_mov_b32_e32 v64, v0
	v_mov_b32_e32 v65, v0
	v_mov_b32_e32 v66, v0
	v_mov_b32_e32 v67, v0
	v_mov_b32_e32 v72, v0
	v_mov_b32_e32 v73, v0
	v_mov_b32_e32 v74, v0
	v_mov_b32_e32 v75, v0
	v_mov_b32_e32 v80, v0
	v_mov_b32_e32 v81, v0
	v_mov_b32_e32 v82, v0
	v_mov_b32_e32 v83, v0
	v_mov_b32_e32 v88, v0
	v_mov_b32_e32 v89, v0
	v_mov_b32_e32 v90, v0
	v_mov_b32_e32 v91, v0
	v_mov_b32_e32 v96, v0
	v_mov_b32_e32 v97, v0
	v_mov_b32_e32 v98, v0
	v_mov_b32_e32 v99, v0
	v_mov_b32_e32 v104, v0
	v_mov_b32_e32 v105, v0
	v_mov_b32_e32 v106, v0
	v_mov_b32_e32 v107, v0
	v_mov_b32_e32 v116, v0
	v_mov_b32_e32 v117, v0
	v_mov_b32_e32 v118, v0
	v_mov_b32_e32 v119, v0
	v_mov_b32_e32 v124, v0
	v_mov_b32_e32 v125, v0
	v_mov_b32_e32 v126, v0
	v_mov_b32_e32 v127, v0
	v_mov_b32_e32 v68, v0
	v_mov_b32_e32 v69, v0
	v_mov_b32_e32 v70, v0
	v_mov_b32_e32 v71, v0
	v_mov_b32_e32 v76, v0
	v_mov_b32_e32 v77, v0
	v_mov_b32_e32 v78, v0
	v_mov_b32_e32 v79, v0
	v_mov_b32_e32 v84, v0
	v_mov_b32_e32 v85, v0
	v_mov_b32_e32 v86, v0
	v_mov_b32_e32 v87, v0
	v_mov_b32_e32 v92, v0
	v_mov_b32_e32 v93, v0
	v_mov_b32_e32 v94, v0
	v_mov_b32_e32 v95, v0
	v_mov_b32_e32 v100, v0
	v_mov_b32_e32 v101, v0
	v_mov_b32_e32 v102, v0
	v_mov_b32_e32 v103, v0
	v_mov_b32_e32 v108, v0
	v_mov_b32_e32 v109, v0
	v_mov_b32_e32 v110, v0
	v_mov_b32_e32 v111, v0
	v_mov_b32_e32 v120, v0
	v_mov_b32_e32 v121, v0
	v_mov_b32_e32 v122, v0
	v_mov_b32_e32 v123, v0
	v_mov_b32_e32 v128, v0
	v_mov_b32_e32 v129, v0
	v_mov_b32_e32 v130, v0
	v_mov_b32_e32 v131, v0
	s_nop 0
	s_nop 0
	s_nop 0
	s_nop 0
	s_nop 0
	s_nop 0
	s_nop 0
	s_nop 0
	s_nop 0
	s_nop 0
	s_nop 0
	s_nop 0
	s_nop 0
	s_nop 0
	s_nop 0

;     __device__ __forceinline__ bool next(int i, Unit& u) const { if (i != 0) return false; return base.next(which, u); }
;     __device__ __forceinline__ bool next(int i, Unit& u) const { if (i >= nrd) return false; u.pm = (rd0 + i) * 16 + 4 * xl + (j >> 3); u.pn = j & 7; return true; }
; template <class Epi, class Sched, bool ALIGN_EPI = false, bool SP2 = false>
; __device__ __forceinline__ void gemm_phase(PG8_LAS unsigned char* lds, const Gemm g, const Sched& S, const Epi& E, const int wave_id) {
;     ...
;         const bool has_next = S.next(ui + 1, nxt);
;         const char* nA = has_next ? (const char*)g.A + (size_t)nxt.pm * tstep : cA; const char* nB = has_next ? (const char*)g.Bt + (size_t)nxt.pn * tstep : cB;
;     ...
; #pragma unroll
;         for (int a = 0; a < 2; ++a)
; #pragma unroll
;             for (int b = 0; b < 2; ++b)
; #pragma unroll
;                 for (int m = 0; m < 4; ++m)
; #pragma unroll
;                     for (int n = 0; n < 2; ++n) acc[a][b][m][n] = (f32x4){0.f, 0.f, 0.f, 0.f};
;         cur = nxt; cA = nA; cB = nB; ++ui;
.LBB0_521:
	s_mov_b32 s49, s0
	s_mov_b32 s1, s0
	s_add_i32 s0, s48, s12
	s_mov_b64 s[46:47], s[40:41]
	s_and_b64 s[40:41], s[10:11], exec
	s_cselect_b32 s40, s0, s49
	s_ashr_i32 s41, s40, 31
	s_lshl_b64 s[40:41], s[40:41], 20
	s_add_u32 s40, s6, s40
	s_addc_u32 s41, s7, s41
	s_and_b64 s[48:49], s[10:11], exec
	s_cselect_b32 vcc_lo, s41, s47
	s_cselect_b32 vcc_hi, s40, s46
	v_lshl_add_u64 v[128:129], s[46:47], 0, v[182:183]
	v_lshl_add_u64 v[130:131], s[46:47], 0, v[184:185]
	s_mov_b32 s58, -2
	s_mov_b64 s[48:49], 0
	v_mov_b32_e32 v0, 0
	v_mov_b32_e32 v1, v177
	v_mov_b32_e32 v2, v177
	v_mov_b32_e32 v3, v177
	v_mov_b32_e32 v4, 0
	v_mov_b32_e32 v5, v177
	v_mov_b32_e32 v6, v177
	v_mov_b32_e32 v7, v177
	v_mov_b32_e32 v16, 0
	v_mov_b32_e32 v17, v177
	v_mov_b32_e32 v18, v177
	v_mov_b32_e32 v19, v177
	v_mov_b32_e32 v20, 0
	v_mov_b32_e32 v21, v177
	v_mov_b32_e32 v22, v177
	v_mov_b32_e32 v23, v177
	v_mov_b32_e32 v32, 0
	v_mov_b32_e32 v33, v177
	v_mov_b32_e32 v34, v177
	v_mov_b32_e32 v35, v177
	v_mov_b32_e32 v36, 0
	v_mov_b32_e32 v37, v177
	v_mov_b32_e32 v38, v177
	v_mov_b32_e32 v39, v177
	v_mov_b32_e32 v48, 0
	v_mov_b32_e32 v49, v177
	v_mov_b32_e32 v50, v177
	v_mov_b32_e32 v51, v177
	v_mov_b32_e32 v52, 0
	v_mov_b32_e32 v53, v177
	v_mov_b32_e32 v54, v177
	v_mov_b32_e32 v55, v177
	v_mov_b32_e32 v8, 0
	v_mov_b32_e32 v9, v177
	v_mov_b32_e32 v10, v177
	v_mov_b32_e32 v11, v177
	v_mov_b32_e32 v12, 0
	v_mov_b32_e32 v13, v177
	v_mov_b32_e32 v14, v177
	v_mov_b32_e32 v15, v177
	v_mov_b32_e32 v24, 0
	v_mov_b32_e32 v25, v177
	v_mov_b32_e32 v26, v177
	v_mov_b32_e32 v27, v177
	v_mov_b32_e32 v28, 0
	v_mov_b32_e32 v29, v177
	v_mov_b32_e32 v30, v177
	v_mov_b32_e32 v31, v177
	v_mov_b32_e32 v40, 0
	v_mov_b32_e32 v41, v177
	v_mov_b32_e32 v42, v177
	v_mov_b32_e32 v43, v177
	v_mov_b32_e32 v44, 0
	v_mov_b32_e32 v45, v177
	v_mov_b32_e32 v46, v177
	v_mov_b32_e32 v47, v177
	v_mov_b32_e32 v56, 0
	v_mov_b32_e32 v57, v177
	v_mov_b32_e32 v58, v177
	v_mov_b32_e32 v59, v177
	v_mov_b32_e32 v60, 0
	v_mov_b32_e32 v61, v177
	v_mov_b32_e32 v62, v177
	v_mov_b32_e32 v63, v177
	v_mov_b32_e32 v64, 0
	v_mov_b32_e32 v65, v177
	v_mov_b32_e32 v66, v177
	v_mov_b32_e32 v67, v177
	v_mov_b32_e32 v68, 0
	v_mov_b32_e32 v69, v177
	v_mov_b32_e32 v70, v177
	v_mov_b32_e32 v71, v177
	v_mov_b32_e32 v80, 0
	v_mov_b32_e32 v81, v177
	v_mov_b32_e32 v82, v177
	v_mov_b32_e32 v83, v177
	v_mov_b32_e32 v84, 0
	v_mov_b32_e32 v85, v177
	v_mov_b32_e32 v86, v177
	v_mov_b32_e32 v87, v177
	v_mov_b32_e32 v96, 0
	v_mov_b32_e32 v97, v177
	v_mov_b32_e32 v98, v177
	v_mov_b32_e32 v99, v177
	v_mov_b32_e32 v100, 0
	v_mov_b32_e32 v101, v177
	v_mov_b32_e32 v102, v177
	v_mov_b32_e32 v103, v177
	v_mov_b32_e32 v112, 0
	v_mov_b32_e32 v113, v177
	v_mov_b32_e32 v114, v177
	v_mov_b32_e32 v115, v177
	v_mov_b32_e32 v116, 0
	v_mov_b32_e32 v117, v177
	v_mov_b32_e32 v118, v177
	v_mov_b32_e32 v119, v177
	v_mov_b32_e32 v72, 0
	v_mov_b32_e32 v73, v177
	v_mov_b32_e32 v74, v177
	v_mov_b32_e32 v75, v177
	v_mov_b32_e32 v76, 0
	v_mov_b32_e32 v77, v177
	v_mov_b32_e32 v78, v177
	v_mov_b32_e32 v79, v177
	v_mov_b32_e32 v88, 0
	v_mov_b32_e32 v89, v177
	v_mov_b32_e32 v90, v177
	v_mov_b32_e32 v91, v177
	v_mov_b32_e32 v92, 0
	v_mov_b32_e32 v93, v177
	v_mov_b32_e32 v94, v177
	v_mov_b32_e32 v95, v177
	v_mov_b32_e32 v104, 0
	v_mov_b32_e32 v105, v177
	v_mov_b32_e32 v106, v177
	v_mov_b32_e32 v107, v177
	v_mov_b32_e32 v108, 0
	v_mov_b32_e32 v109, v177
	v_mov_b32_e32 v110, v177
	v_mov_b32_e32 v111, v177
	v_mov_b32_e32 v120, 0
	v_mov_b32_e32 v121, v177
	v_mov_b32_e32 v122, v177
	v_mov_b32_e32 v123, v177
	v_mov_b32_e32 v124, 0
	v_mov_b32_e32 v125, v177
	v_mov_b32_e32 v126, v177
	v_mov_b32_e32 v127, v177
	s_nop 0
	s_nop 0
	s_nop 0
	s_nop 0
	s_nop 0
	s_nop 0
	s_nop 0
	s_nop 0
	s_nop 0
